# grid barrier: L1 invalidate issued right behind the arrival atomic (its latency overlaps the atomic round trip instead of delaying arrival)
# speedup vs baseline: 1.0009x; 1.0009x over previous
; __device__ __forceinline__ unsigned xb_add(unsigned* p, unsigned v) { return __hip_atomic_fetch_add(p, v, __ATOMIC_RELAXED, __HIP_MEMORY_SCOPE_AGENT); }
; __device__ __forceinline__ void xcd_barrier(const XcdBarrier& b) {
;     ...
;         const unsigned old = xb_add(&bar[XB_XSUB(b.x)], 1u);
;         const unsigned gen = old / nloc;
;         if (old + 1u == (gen + 1u) * nloc) {
;             __builtin_amdgcn_fence(__ATOMIC_RELEASE, "agent");
;             asm volatile("s_waitcnt vmcnt(0)" ::: "memory");
;             const unsigned og = xb_add(&bar[XB_TOP], 1u);
.LBB0_455:
	s_mov_b64 s[2:3], exec
	v_mbcnt_lo_u32_b32 v1, s2, 0
	v_mbcnt_hi_u32_b32 v1, s3, v1
	s_lshl_b32 s17, s17, 6
	v_cmp_eq_u32_e32 vcc, 0, v1
	s_and_saveexec_b64 s[4:5], vcc
	s_cbranch_execz .LBB0_457
	s_add_i32 s88, s17, 0x500
	s_lshl_b64 s[8:9], s[88:89], 2
	v_readlane_b32 s18, v245, 29
	s_add_u32 s8, s18, s8
	v_readlane_b32 s18, v245, 30
	s_addc_u32 s9, s18, s9
	s_bcnt1_i32_b64 s2, s[2:3]
	v_mov_b32_e32 v4, s2
	global_atomic_add v4, v0, v4, s[8:9] sc0
	buffer_inv sc1
